# conv cross-item software pipeline: next item's 16 staging loads issued after the staging barrier
# baseline (speedup 1.0000x reference)
.LBB0_480:
	v_lshl_add_u32 v8, s0, 6, v56
	s_mov_b32 s2, 0x10000
	v_cmp_gt_i32_e64 s[2:3], s2, v8
	v_mov_b32_e32 v14, 0
	v_mov_b32_e32 v15, 0
	v_cndmask_b32_e64 v9, v227, v252, s[2:3]
	v_and_b32_e32 v9, v9, v8
	v_add_u32_e32 v84, -15, v9
	v_cndmask_b32_e64 v83, v223, v230, s[2:3]
	v_sub_u32_e32 v82, v8, v9
	v_readlane_b32 s2, v253, 5
	s_nop 1
	s_cmp_lg_u32 s0, s2
	s_cbranch_scc1 .Lcv_have
	v_add_u32_e32 v206, v84, v57
	v_cmp_lt_u32_e64 s[2:3], v206, v83
	s_and_saveexec_b64 s[4:5], s[2:3]
	v_add_u32_e32 v8, v206, v82
	v_ashrrev_i32_e32 v9, 31, v8
	v_lshlrev_b64 v[8:9], 9, v[8:9]
	v_lshl_add_u64 v[10:11], v[18:19], 0, v[8:9]
	v_lshl_add_u64 v[12:13], v[20:21], 0, v[8:9]
	global_load_dwordx4 v[148:151], v[10:11], off
	global_load_dwordx4 v[152:155], v[12:13], off
	s_mov_b64 exec, s[4:5]
	v_add_u32_e32 v206, v84, v65
	v_cmp_lt_u32_e64 s[2:3], v206, v83
	s_and_saveexec_b64 s[4:5], s[2:3]
	v_add_u32_e32 v8, v206, v82
	v_ashrrev_i32_e32 v9, 31, v8
	v_lshlrev_b64 v[8:9], 9, v[8:9]
	v_lshl_add_u64 v[10:11], v[18:19], 0, v[8:9]
	v_lshl_add_u64 v[12:13], v[20:21], 0, v[8:9]
	global_load_dwordx4 v[156:159], v[10:11], off
	global_load_dwordx4 v[160:163], v[12:13], off
	s_mov_b64 exec, s[4:5]
	v_add_u32_e32 v206, v84, v66
	v_cmp_lt_u32_e64 s[2:3], v206, v83
	s_and_saveexec_b64 s[4:5], s[2:3]
	v_add_u32_e32 v8, v206, v82
	v_ashrrev_i32_e32 v9, 31, v8
	v_lshlrev_b64 v[8:9], 9, v[8:9]
	v_lshl_add_u64 v[10:11], v[18:19], 0, v[8:9]
	v_lshl_add_u64 v[12:13], v[20:21], 0, v[8:9]
	global_load_dwordx4 v[164:167], v[10:11], off
	global_load_dwordx4 v[168:171], v[12:13], off
	s_mov_b64 exec, s[4:5]
	v_add_u32_e32 v206, v84, v67
	v_cmp_lt_u32_e64 s[2:3], v206, v83
	s_and_saveexec_b64 s[4:5], s[2:3]
	v_add_u32_e32 v8, v206, v82
	v_ashrrev_i32_e32 v9, 31, v8
	v_lshlrev_b64 v[8:9], 9, v[8:9]
	v_lshl_add_u64 v[10:11], v[18:19], 0, v[8:9]
	v_lshl_add_u64 v[12:13], v[20:21], 0, v[8:9]
	global_load_dwordx4 v[172:175], v[10:11], off
	global_load_dwordx4 v[176:179], v[12:13], off
	s_mov_b64 exec, s[4:5]
	v_add_u32_e32 v206, v84, v68
	v_cmp_lt_u32_e64 s[2:3], v206, v83
	s_and_saveexec_b64 s[4:5], s[2:3]
	v_add_u32_e32 v8, v206, v82
	v_ashrrev_i32_e32 v9, 31, v8
	v_lshlrev_b64 v[8:9], 9, v[8:9]
	v_lshl_add_u64 v[10:11], v[18:19], 0, v[8:9]
	v_lshl_add_u64 v[12:13], v[20:21], 0, v[8:9]
	global_load_dwordx4 v[180:183], v[10:11], off
	global_load_dwordx4 v[184:187], v[12:13], off
	s_mov_b64 exec, s[4:5]
	v_add_u32_e32 v206, v84, v69
	v_cmp_lt_u32_e64 s[2:3], v206, v83
	s_and_saveexec_b64 s[4:5], s[2:3]
	v_add_u32_e32 v8, v206, v82
	v_ashrrev_i32_e32 v9, 31, v8
	v_lshlrev_b64 v[8:9], 9, v[8:9]
	v_lshl_add_u64 v[10:11], v[18:19], 0, v[8:9]
	v_lshl_add_u64 v[12:13], v[20:21], 0, v[8:9]
	global_load_dwordx4 v[188:191], v[10:11], off
	global_load_dwordx4 v[208:211], v[12:13], off
	s_mov_b64 exec, s[4:5]
	v_add_u32_e32 v206, v84, v70
	v_cmp_lt_u32_e64 s[2:3], v206, v83
	s_and_saveexec_b64 s[4:5], s[2:3]
	v_add_u32_e32 v8, v206, v82
	v_ashrrev_i32_e32 v9, 31, v8
	v_lshlrev_b64 v[8:9], 9, v[8:9]
	v_lshl_add_u64 v[10:11], v[18:19], 0, v[8:9]
	v_lshl_add_u64 v[12:13], v[20:21], 0, v[8:9]
	global_load_dwordx4 v[212:215], v[10:11], off
	global_load_dwordx4 v[216:219], v[12:13], off
	s_mov_b64 exec, s[4:5]
	v_add_u32_e32 v206, v84, v71
	v_cmp_lt_u32_e64 s[2:3], v206, v83
	s_and_b64 s[2:3], s[2:3], vcc
	s_and_saveexec_b64 s[4:5], s[2:3]
	v_add_u32_e32 v8, v206, v82
	v_ashrrev_i32_e32 v9, 31, v8
	v_lshlrev_b64 v[8:9], 9, v[8:9]
	v_lshl_add_u64 v[10:11], v[18:19], 0, v[8:9]
	v_lshl_add_u64 v[12:13], v[20:21], 0, v[8:9]
	global_load_dwordx4 v[244:247], v[10:11], off
	global_load_dwordx4 v[248:251], v[12:13], off
	s_mov_b64 exec, s[4:5]
.Lcv_have:
	s_waitcnt vmcnt(0)
	v_mov_b64_e32 v[8:9], 0
	v_mov_b64_e32 v[10:11], 0
	v_mov_b64_e32 v[12:13], 0
	v_mov_b64_e32 v[14:15], 0
	v_add_u32_e32 v206, v84, v57
	v_cmp_lt_u32_e64 s[2:3], v206, v83
	s_and_saveexec_b64 s[4:5], s[2:3]
	v_lshlrev_b32_e32 v16, 16, v148
	v_and_b32_e32 v17, 0xffff0000, v148
	v_lshlrev_b32_e32 v146, 16, v152
	v_and_b32_e32 v147, 0xffff0000, v152
	v_pk_mul_f32 v[8:9], v[16:17], v[146:147]
	v_lshlrev_b32_e32 v16, 16, v149
	v_and_b32_e32 v17, 0xffff0000, v149
	v_lshlrev_b32_e32 v146, 16, v153
	v_and_b32_e32 v147, 0xffff0000, v153
	v_pk_mul_f32 v[10:11], v[16:17], v[146:147]
	v_lshlrev_b32_e32 v16, 16, v150
	v_and_b32_e32 v17, 0xffff0000, v150
	v_lshlrev_b32_e32 v146, 16, v154
	v_and_b32_e32 v147, 0xffff0000, v154
	v_pk_mul_f32 v[12:13], v[16:17], v[146:147]
	v_lshlrev_b32_e32 v16, 16, v151
	v_and_b32_e32 v17, 0xffff0000, v151
	v_lshlrev_b32_e32 v146, 16, v155
	v_and_b32_e32 v147, 0xffff0000, v155
	v_pk_mul_f32 v[14:15], v[16:17], v[146:147]
	s_mov_b64 exec, s[4:5]
	ds_write_b128 v74, v[8:11]
	ds_write_b128 v74, v[12:15] offset:16
	v_mov_b64_e32 v[86:87], 0
	v_mov_b64_e32 v[88:89], 0
	v_mov_b64_e32 v[90:91], 0
	v_mov_b64_e32 v[92:93], 0
	v_add_u32_e32 v206, v84, v65
	v_cmp_lt_u32_e64 s[2:3], v206, v83
	s_and_saveexec_b64 s[4:5], s[2:3]
	v_lshlrev_b32_e32 v16, 16, v156
	v_and_b32_e32 v17, 0xffff0000, v156
	v_lshlrev_b32_e32 v146, 16, v160
	v_and_b32_e32 v147, 0xffff0000, v160
	v_pk_mul_f32 v[86:87], v[16:17], v[146:147]
	v_lshlrev_b32_e32 v16, 16, v157
	v_and_b32_e32 v17, 0xffff0000, v157
	v_lshlrev_b32_e32 v146, 16, v161
	v_and_b32_e32 v147, 0xffff0000, v161
	v_pk_mul_f32 v[88:89], v[16:17], v[146:147]
	v_lshlrev_b32_e32 v16, 16, v158
	v_and_b32_e32 v17, 0xffff0000, v158
	v_lshlrev_b32_e32 v146, 16, v162
	v_and_b32_e32 v147, 0xffff0000, v162
	v_pk_mul_f32 v[90:91], v[16:17], v[146:147]
	v_lshlrev_b32_e32 v16, 16, v159
	v_and_b32_e32 v17, 0xffff0000, v159
	v_lshlrev_b32_e32 v146, 16, v163
	v_and_b32_e32 v147, 0xffff0000, v163
	v_pk_mul_f32 v[92:93], v[16:17], v[146:147]
	s_mov_b64 exec, s[4:5]
	ds_write_b128 v75, v[86:89]
	ds_write_b128 v75, v[90:93] offset:16
	v_mov_b64_e32 v[8:9], 0
	v_mov_b64_e32 v[10:11], 0
	v_mov_b64_e32 v[12:13], 0
	v_mov_b64_e32 v[14:15], 0
	v_add_u32_e32 v206, v84, v66
	v_cmp_lt_u32_e64 s[2:3], v206, v83
	s_and_saveexec_b64 s[4:5], s[2:3]
	v_lshlrev_b32_e32 v16, 16, v164
	v_and_b32_e32 v17, 0xffff0000, v164
	v_lshlrev_b32_e32 v146, 16, v168
	v_and_b32_e32 v147, 0xffff0000, v168
	v_pk_mul_f32 v[8:9], v[16:17], v[146:147]
	v_lshlrev_b32_e32 v16, 16, v165
	v_and_b32_e32 v17, 0xffff0000, v165
	v_lshlrev_b32_e32 v146, 16, v169
	v_and_b32_e32 v147, 0xffff0000, v169
	v_pk_mul_f32 v[10:11], v[16:17], v[146:147]
	v_lshlrev_b32_e32 v16, 16, v166
	v_and_b32_e32 v17, 0xffff0000, v166
	v_lshlrev_b32_e32 v146, 16, v170
	v_and_b32_e32 v147, 0xffff0000, v170
	v_pk_mul_f32 v[12:13], v[16:17], v[146:147]
	v_lshlrev_b32_e32 v16, 16, v167
	v_and_b32_e32 v17, 0xffff0000, v167
	v_lshlrev_b32_e32 v146, 16, v171
	v_and_b32_e32 v147, 0xffff0000, v171
	v_pk_mul_f32 v[14:15], v[16:17], v[146:147]
	s_mov_b64 exec, s[4:5]
	ds_write_b128 v76, v[8:11]
	ds_write_b128 v76, v[12:15] offset:16
	v_mov_b64_e32 v[86:87], 0
	v_mov_b64_e32 v[88:89], 0
	v_mov_b64_e32 v[90:91], 0
	v_mov_b64_e32 v[92:93], 0
	v_add_u32_e32 v206, v84, v67
	v_cmp_lt_u32_e64 s[2:3], v206, v83
	s_and_saveexec_b64 s[4:5], s[2:3]
	v_lshlrev_b32_e32 v16, 16, v172
	v_and_b32_e32 v17, 0xffff0000, v172
	v_lshlrev_b32_e32 v146, 16, v176
	v_and_b32_e32 v147, 0xffff0000, v176
	v_pk_mul_f32 v[86:87], v[16:17], v[146:147]
	v_lshlrev_b32_e32 v16, 16, v173
	v_and_b32_e32 v17, 0xffff0000, v173
	v_lshlrev_b32_e32 v146, 16, v177
	v_and_b32_e32 v147, 0xffff0000, v177
	v_pk_mul_f32 v[88:89], v[16:17], v[146:147]
	v_lshlrev_b32_e32 v16, 16, v174
	v_and_b32_e32 v17, 0xffff0000, v174
	v_lshlrev_b32_e32 v146, 16, v178
	v_and_b32_e32 v147, 0xffff0000, v178
	v_pk_mul_f32 v[90:91], v[16:17], v[146:147]
	v_lshlrev_b32_e32 v16, 16, v175
	v_and_b32_e32 v17, 0xffff0000, v175
	v_lshlrev_b32_e32 v146, 16, v179
	v_and_b32_e32 v147, 0xffff0000, v179
	v_pk_mul_f32 v[92:93], v[16:17], v[146:147]
	s_mov_b64 exec, s[4:5]
	ds_write_b128 v77, v[86:89]
	ds_write_b128 v77, v[90:93] offset:16
	v_mov_b64_e32 v[8:9], 0
	v_mov_b64_e32 v[10:11], 0
	v_mov_b64_e32 v[12:13], 0
	v_mov_b64_e32 v[14:15], 0
	v_add_u32_e32 v206, v84, v68
	v_cmp_lt_u32_e64 s[2:3], v206, v83
	s_and_saveexec_b64 s[4:5], s[2:3]
	v_lshlrev_b32_e32 v16, 16, v180
	v_and_b32_e32 v17, 0xffff0000, v180
	v_lshlrev_b32_e32 v146, 16, v184
	v_and_b32_e32 v147, 0xffff0000, v184
	v_pk_mul_f32 v[8:9], v[16:17], v[146:147]
	v_lshlrev_b32_e32 v16, 16, v181
	v_and_b32_e32 v17, 0xffff0000, v181
	v_lshlrev_b32_e32 v146, 16, v185
	v_and_b32_e32 v147, 0xffff0000, v185
	v_pk_mul_f32 v[10:11], v[16:17], v[146:147]
	v_lshlrev_b32_e32 v16, 16, v182
	v_and_b32_e32 v17, 0xffff0000, v182
	v_lshlrev_b32_e32 v146, 16, v186
	v_and_b32_e32 v147, 0xffff0000, v186
	v_pk_mul_f32 v[12:13], v[16:17], v[146:147]
	v_lshlrev_b32_e32 v16, 16, v183
	v_and_b32_e32 v17, 0xffff0000, v183
	v_lshlrev_b32_e32 v146, 16, v187
	v_and_b32_e32 v147, 0xffff0000, v187
	v_pk_mul_f32 v[14:15], v[16:17], v[146:147]
	s_mov_b64 exec, s[4:5]
	ds_write_b128 v78, v[8:11]
	ds_write_b128 v78, v[12:15] offset:16
	v_mov_b64_e32 v[86:87], 0
	v_mov_b64_e32 v[88:89], 0
	v_mov_b64_e32 v[90:91], 0
	v_mov_b64_e32 v[92:93], 0
	v_add_u32_e32 v206, v84, v69
	v_cmp_lt_u32_e64 s[2:3], v206, v83
	s_and_saveexec_b64 s[4:5], s[2:3]
	v_lshlrev_b32_e32 v16, 16, v188
	v_and_b32_e32 v17, 0xffff0000, v188
	v_lshlrev_b32_e32 v146, 16, v208
	v_and_b32_e32 v147, 0xffff0000, v208
	v_pk_mul_f32 v[86:87], v[16:17], v[146:147]
	v_lshlrev_b32_e32 v16, 16, v189
	v_and_b32_e32 v17, 0xffff0000, v189
	v_lshlrev_b32_e32 v146, 16, v209
	v_and_b32_e32 v147, 0xffff0000, v209
	v_pk_mul_f32 v[88:89], v[16:17], v[146:147]
	v_lshlrev_b32_e32 v16, 16, v190
	v_and_b32_e32 v17, 0xffff0000, v190
	v_lshlrev_b32_e32 v146, 16, v210
	v_and_b32_e32 v147, 0xffff0000, v210
	v_pk_mul_f32 v[90:91], v[16:17], v[146:147]
	v_lshlrev_b32_e32 v16, 16, v191
	v_and_b32_e32 v17, 0xffff0000, v191
	v_lshlrev_b32_e32 v146, 16, v211
	v_and_b32_e32 v147, 0xffff0000, v211
	v_pk_mul_f32 v[92:93], v[16:17], v[146:147]
	s_mov_b64 exec, s[4:5]
	ds_write_b128 v79, v[86:89]
	ds_write_b128 v79, v[90:93] offset:16
	v_mov_b64_e32 v[8:9], 0
	v_mov_b64_e32 v[10:11], 0
	v_mov_b64_e32 v[12:13], 0
	v_mov_b64_e32 v[14:15], 0
	v_add_u32_e32 v206, v84, v70
	v_cmp_lt_u32_e64 s[2:3], v206, v83
	s_and_saveexec_b64 s[4:5], s[2:3]
	v_lshlrev_b32_e32 v16, 16, v212
	v_and_b32_e32 v17, 0xffff0000, v212
	v_lshlrev_b32_e32 v146, 16, v216
	v_and_b32_e32 v147, 0xffff0000, v216
	v_pk_mul_f32 v[8:9], v[16:17], v[146:147]
	v_lshlrev_b32_e32 v16, 16, v213
	v_and_b32_e32 v17, 0xffff0000, v213
	v_lshlrev_b32_e32 v146, 16, v217
	v_and_b32_e32 v147, 0xffff0000, v217
	v_pk_mul_f32 v[10:11], v[16:17], v[146:147]
	v_lshlrev_b32_e32 v16, 16, v214
	v_and_b32_e32 v17, 0xffff0000, v214
	v_lshlrev_b32_e32 v146, 16, v218
	v_and_b32_e32 v147, 0xffff0000, v218
	v_pk_mul_f32 v[12:13], v[16:17], v[146:147]
	v_lshlrev_b32_e32 v16, 16, v215
	v_and_b32_e32 v17, 0xffff0000, v215
	v_lshlrev_b32_e32 v146, 16, v219
	v_and_b32_e32 v147, 0xffff0000, v219
	v_pk_mul_f32 v[14:15], v[16:17], v[146:147]
	s_mov_b64 exec, s[4:5]
	ds_write_b128 v80, v[8:11]
	ds_write_b128 v80, v[12:15] offset:16
	s_and_saveexec_b64 s[6:7], vcc
	v_mov_b64_e32 v[86:87], 0
	v_mov_b64_e32 v[88:89], 0
	v_mov_b64_e32 v[90:91], 0
	v_mov_b64_e32 v[92:93], 0
	v_add_u32_e32 v206, v84, v71
	v_cmp_lt_u32_e64 s[2:3], v206, v83
	s_and_saveexec_b64 s[4:5], s[2:3]
	v_lshlrev_b32_e32 v16, 16, v244
	v_and_b32_e32 v17, 0xffff0000, v244
	v_lshlrev_b32_e32 v146, 16, v248
	v_and_b32_e32 v147, 0xffff0000, v248
	v_pk_mul_f32 v[86:87], v[16:17], v[146:147]
	v_lshlrev_b32_e32 v16, 16, v245
	v_and_b32_e32 v17, 0xffff0000, v245
	v_lshlrev_b32_e32 v146, 16, v249
	v_and_b32_e32 v147, 0xffff0000, v249
	v_pk_mul_f32 v[88:89], v[16:17], v[146:147]
	v_lshlrev_b32_e32 v16, 16, v246
	v_and_b32_e32 v17, 0xffff0000, v246
	v_lshlrev_b32_e32 v146, 16, v250
	v_and_b32_e32 v147, 0xffff0000, v250
	v_pk_mul_f32 v[90:91], v[16:17], v[146:147]
	v_lshlrev_b32_e32 v16, 16, v247
	v_and_b32_e32 v17, 0xffff0000, v247
	v_lshlrev_b32_e32 v146, 16, v251
	v_and_b32_e32 v147, 0xffff0000, v251
	v_pk_mul_f32 v[92:93], v[16:17], v[146:147]
	s_mov_b64 exec, s[4:5]
	ds_write_b128 v81, v[86:89]
	ds_write_b128 v81, v[90:93] offset:16
	s_mov_b64 exec, s[6:7]
	s_waitcnt lgkmcnt(0)
	s_barrier
	ds_read2st64_b32 v[8:9], v58 offset1:4
	ds_read2st64_b32 v[10:11], v58 offset0:8 offset1:12
	ds_read2st64_b32 v[12:13], v58 offset0:16 offset1:20
	ds_read2st64_b32 v[14:15], v58 offset0:24 offset1:28
	ds_read2st64_b32 v[16:17], v58 offset0:32 offset1:36
	s_waitcnt vmcnt(2) lgkmcnt(4)
	v_readlane_b32 s98, v253, 0
	s_nop 1
	s_add_i32 s98, s0, s98
	s_cmpk_gt_i32 s98, 0x4ff
	s_cbranch_scc1 .Lcv_nopf
	v_lshl_add_u32 v146, s98, 6, v56
	s_mov_b32 s99, 0x10000
	v_cmp_gt_i32_e64 s[100:101], s99, v146
	s_nop 1
	v_cndmask_b32_e64 v147, v227, v252, s[100:101]
	v_and_b32_e32 v147, v147, v146
	v_cndmask_b32_e64 v207, v223, v230, s[100:101]
	v_sub_u32_e32 v146, v146, v147
	v_add_u32_e32 v147, -15, v147
	v_add_u32_e32 v206, v147, v57
	v_cmp_lt_u32_e64 s[98:99], v206, v207
	s_and_saveexec_b64 s[100:101], s[98:99]
	v_add_u32_e32 v152, v206, v146
	v_ashrrev_i32_e32 v153, 31, v152
	v_lshlrev_b64 v[152:153], 9, v[152:153]
	v_lshl_add_u64 v[154:155], v[20:21], 0, v[152:153]
	v_lshl_add_u64 v[152:153], v[18:19], 0, v[152:153]
	global_load_dwordx4 v[148:151], v[152:153], off
	global_load_dwordx4 v[152:155], v[154:155], off
	s_mov_b64 exec, s[100:101]
	v_add_u32_e32 v206, v147, v65
	v_cmp_lt_u32_e64 s[98:99], v206, v207
	s_and_saveexec_b64 s[100:101], s[98:99]
	v_add_u32_e32 v160, v206, v146
	v_ashrrev_i32_e32 v161, 31, v160
	v_lshlrev_b64 v[160:161], 9, v[160:161]
	v_lshl_add_u64 v[162:163], v[20:21], 0, v[160:161]
	v_lshl_add_u64 v[160:161], v[18:19], 0, v[160:161]
	global_load_dwordx4 v[156:159], v[160:161], off
	global_load_dwordx4 v[160:163], v[162:163], off
	s_mov_b64 exec, s[100:101]
	v_add_u32_e32 v206, v147, v66
	v_cmp_lt_u32_e64 s[98:99], v206, v207
	s_and_saveexec_b64 s[100:101], s[98:99]
	v_add_u32_e32 v168, v206, v146
	v_ashrrev_i32_e32 v169, 31, v168
	v_lshlrev_b64 v[168:169], 9, v[168:169]
	v_lshl_add_u64 v[170:171], v[20:21], 0, v[168:169]
	v_lshl_add_u64 v[168:169], v[18:19], 0, v[168:169]
	global_load_dwordx4 v[164:167], v[168:169], off
	global_load_dwordx4 v[168:171], v[170:171], off
	s_mov_b64 exec, s[100:101]
	v_add_u32_e32 v206, v147, v67
	v_cmp_lt_u32_e64 s[98:99], v206, v207
	s_and_saveexec_b64 s[100:101], s[98:99]
	v_add_u32_e32 v176, v206, v146
	v_ashrrev_i32_e32 v177, 31, v176
	v_lshlrev_b64 v[176:177], 9, v[176:177]
	v_lshl_add_u64 v[178:179], v[20:21], 0, v[176:177]
	v_lshl_add_u64 v[176:177], v[18:19], 0, v[176:177]
	global_load_dwordx4 v[172:175], v[176:177], off
	global_load_dwordx4 v[176:179], v[178:179], off
	s_mov_b64 exec, s[100:101]
	v_add_u32_e32 v206, v147, v68
	v_cmp_lt_u32_e64 s[98:99], v206, v207
	s_and_saveexec_b64 s[100:101], s[98:99]
	v_add_u32_e32 v184, v206, v146
	v_ashrrev_i32_e32 v185, 31, v184
	v_lshlrev_b64 v[184:185], 9, v[184:185]
	v_lshl_add_u64 v[186:187], v[20:21], 0, v[184:185]
	v_lshl_add_u64 v[184:185], v[18:19], 0, v[184:185]
	global_load_dwordx4 v[180:183], v[184:185], off
	global_load_dwordx4 v[184:187], v[186:187], off
	s_mov_b64 exec, s[100:101]
	v_add_u32_e32 v206, v147, v69
	v_cmp_lt_u32_e64 s[98:99], v206, v207
	s_and_saveexec_b64 s[100:101], s[98:99]
	v_add_u32_e32 v208, v206, v146
	v_ashrrev_i32_e32 v209, 31, v208
	v_lshlrev_b64 v[208:209], 9, v[208:209]
	v_lshl_add_u64 v[210:211], v[20:21], 0, v[208:209]
	v_lshl_add_u64 v[208:209], v[18:19], 0, v[208:209]
	global_load_dwordx4 v[188:191], v[208:209], off
	global_load_dwordx4 v[208:211], v[210:211], off
	s_mov_b64 exec, s[100:101]
	v_add_u32_e32 v206, v147, v70
	v_cmp_lt_u32_e64 s[98:99], v206, v207
	s_and_saveexec_b64 s[100:101], s[98:99]
	v_add_u32_e32 v216, v206, v146
	v_ashrrev_i32_e32 v217, 31, v216
	v_lshlrev_b64 v[216:217], 9, v[216:217]
	v_lshl_add_u64 v[218:219], v[20:21], 0, v[216:217]
	v_lshl_add_u64 v[216:217], v[18:19], 0, v[216:217]
	global_load_dwordx4 v[212:215], v[216:217], off
	global_load_dwordx4 v[216:219], v[218:219], off
	s_mov_b64 exec, s[100:101]
	v_add_u32_e32 v206, v147, v71
	v_cmp_lt_u32_e64 s[98:99], v206, v207
	s_and_b64 s[98:99], s[98:99], vcc
	s_and_saveexec_b64 s[100:101], s[98:99]
	v_add_u32_e32 v248, v206, v146
	v_ashrrev_i32_e32 v249, 31, v248
	v_lshlrev_b64 v[248:249], 9, v[248:249]
	v_lshl_add_u64 v[250:251], v[20:21], 0, v[248:249]
	v_lshl_add_u64 v[248:249], v[18:19], 0, v[248:249]
	global_load_dwordx4 v[244:247], v[248:249], off
	global_load_dwordx4 v[248:251], v[250:251], off
	s_mov_b64 exec, s[100:101]
.Lcv_nopf:
	v_fma_f32 v8, v8, v24, v55
	v_fmac_f32_e32 v8, v9, v25
	v_fma_f32 v9, v9, v24, v55
	s_waitcnt lgkmcnt(3)
	v_fmac_f32_e32 v8, v10, v26
	v_fmac_f32_e32 v9, v10, v25
	v_fma_f32 v10, v10, v24, v55
	v_fmac_f32_e32 v8, v11, v27
	v_fmac_f32_e32 v9, v11, v26
	v_fmac_f32_e32 v10, v11, v25
	v_fma_f32 v11, v11, v24, v55
	s_waitcnt lgkmcnt(2)
	v_fmac_f32_e32 v8, v12, v28
	v_fmac_f32_e32 v9, v12, v27
	v_fmac_f32_e32 v10, v12, v26
	v_fmac_f32_e32 v11, v12, v25
	v_fma_f32 v12, v12, v24, v55
	v_fmac_f32_e32 v8, v13, v29
	v_fmac_f32_e32 v9, v13, v28
	v_fmac_f32_e32 v10, v13, v27
	v_fmac_f32_e32 v11, v13, v26
	v_fmac_f32_e32 v12, v13, v25
	v_fma_f32 v13, v13, v24, v55
	ds_read2st64_b32 v[82:83], v58 offset0:40 offset1:44
	s_waitcnt lgkmcnt(2)
	v_fmac_f32_e32 v8, v14, v30
	v_fmac_f32_e32 v9, v14, v29
	v_fmac_f32_e32 v10, v14, v28
	v_fmac_f32_e32 v11, v14, v27
	v_fmac_f32_e32 v12, v14, v26
	v_fmac_f32_e32 v13, v14, v25
	v_fma_f32 v14, v14, v24, v55
	v_fmac_f32_e32 v8, v15, v31
	v_fmac_f32_e32 v9, v15, v30
	v_fmac_f32_e32 v10, v15, v29
	v_fmac_f32_e32 v11, v15, v28
	v_fmac_f32_e32 v12, v15, v27
	v_fmac_f32_e32 v13, v15, v26
	v_fmac_f32_e32 v14, v15, v25
	v_fma_f32 v15, v15, v24, v55
	ds_read2st64_b32 v[84:85], v58 offset0:48 offset1:52
	s_waitcnt lgkmcnt(2)
	v_fmac_f32_e32 v8, v16, v32
	v_fmac_f32_e32 v9, v16, v31
	v_fmac_f32_e32 v10, v16, v30
	v_fmac_f32_e32 v11, v16, v29
	v_fmac_f32_e32 v12, v16, v28
	v_fmac_f32_e32 v13, v16, v27
	v_fmac_f32_e32 v14, v16, v26
	v_fmac_f32_e32 v15, v16, v25
	v_fma_f32 v16, v16, v24, v55
	v_fmac_f32_e32 v8, v17, v33
	v_fmac_f32_e32 v9, v17, v32
	v_fmac_f32_e32 v10, v17, v31
	v_fmac_f32_e32 v11, v17, v30
	v_fmac_f32_e32 v12, v17, v29
	v_fmac_f32_e32 v13, v17, v28
	v_fmac_f32_e32 v14, v17, v27
	v_fmac_f32_e32 v15, v17, v26
	v_fmac_f32_e32 v16, v17, v25
	v_fma_f32 v17, v17, v24, v55
	ds_read2st64_b32 v[86:87], v58 offset0:56 offset1:60
	s_waitcnt lgkmcnt(2)
	v_fmac_f32_e32 v8, v82, v34
	v_fmac_f32_e32 v9, v82, v33
	v_fmac_f32_e32 v10, v82, v32
	v_fmac_f32_e32 v11, v82, v31
	v_fmac_f32_e32 v12, v82, v30
	v_fmac_f32_e32 v13, v82, v29
	v_fmac_f32_e32 v14, v82, v28
	v_fmac_f32_e32 v15, v82, v27
	v_fmac_f32_e32 v16, v82, v26
	v_fmac_f32_e32 v17, v82, v25
	v_fma_f32 v82, v82, v24, v55
	v_fmac_f32_e32 v8, v83, v35
	v_fmac_f32_e32 v9, v83, v34
	v_fmac_f32_e32 v10, v83, v33
	v_fmac_f32_e32 v11, v83, v32
	v_fmac_f32_e32 v12, v83, v31
	v_fmac_f32_e32 v13, v83, v30
	v_fmac_f32_e32 v14, v83, v29
	v_fmac_f32_e32 v15, v83, v28
	v_fmac_f32_e32 v16, v83, v27
	v_fmac_f32_e32 v17, v83, v26
	v_fmac_f32_e32 v82, v83, v25
	v_fma_f32 v83, v83, v24, v55
	ds_read2st64_b32 v[88:89], v58 offset0:64 offset1:68
	s_waitcnt lgkmcnt(2)
	v_fmac_f32_e32 v8, v84, v36
	v_fmac_f32_e32 v9, v84, v35
	v_fmac_f32_e32 v10, v84, v34
	v_fmac_f32_e32 v11, v84, v33
	v_fmac_f32_e32 v12, v84, v32
	v_fmac_f32_e32 v13, v84, v31
	v_fmac_f32_e32 v14, v84, v30
	v_fmac_f32_e32 v15, v84, v29
	v_fmac_f32_e32 v16, v84, v28
	v_fmac_f32_e32 v17, v84, v27
	v_fmac_f32_e32 v82, v84, v26
	v_fmac_f32_e32 v83, v84, v25
	v_fma_f32 v84, v84, v24, v55
	v_fmac_f32_e32 v8, v85, v37
	v_fmac_f32_e32 v9, v85, v36
	v_fmac_f32_e32 v10, v85, v35
	v_fmac_f32_e32 v11, v85, v34
	v_fmac_f32_e32 v12, v85, v33
	v_fmac_f32_e32 v13, v85, v32
	v_fmac_f32_e32 v14, v85, v31
	v_fmac_f32_e32 v15, v85, v30
	v_fmac_f32_e32 v16, v85, v29
	v_fmac_f32_e32 v17, v85, v28
	v_fmac_f32_e32 v82, v85, v27
	v_fmac_f32_e32 v83, v85, v26
	v_fmac_f32_e32 v84, v85, v25
	v_fma_f32 v85, v85, v24, v55
	ds_read2st64_b32 v[90:91], v58 offset0:72 offset1:76
	s_waitcnt lgkmcnt(2)
	v_fmac_f32_e32 v8, v86, v38
	v_fmac_f32_e32 v9, v86, v37
	v_fmac_f32_e32 v10, v86, v36
	v_fmac_f32_e32 v11, v86, v35
	v_fmac_f32_e32 v12, v86, v34
	v_fmac_f32_e32 v13, v86, v33
	v_fmac_f32_e32 v14, v86, v32
	v_fmac_f32_e32 v15, v86, v31
	v_fmac_f32_e32 v16, v86, v30
	v_fmac_f32_e32 v17, v86, v29
	v_fmac_f32_e32 v82, v86, v28
	v_fmac_f32_e32 v83, v86, v27
	v_fmac_f32_e32 v84, v86, v26
	v_fmac_f32_e32 v85, v86, v25
	v_fma_f32 v86, v86, v24, v55
	v_fmac_f32_e32 v8, v87, v39
	v_fmac_f32_e32 v9, v87, v38
	v_fmac_f32_e32 v10, v87, v37
	v_fmac_f32_e32 v11, v87, v36
	v_fmac_f32_e32 v12, v87, v35
	v_fmac_f32_e32 v13, v87, v34
	v_fmac_f32_e32 v14, v87, v33
	v_fmac_f32_e32 v15, v87, v32
	v_fmac_f32_e32 v16, v87, v31
	v_fmac_f32_e32 v17, v87, v30
	v_fmac_f32_e32 v82, v87, v29
	v_fmac_f32_e32 v83, v87, v28
	v_fmac_f32_e32 v84, v87, v27
	v_fmac_f32_e32 v85, v87, v26
	v_fmac_f32_e32 v86, v87, v25
	v_fma_f32 v87, v87, v24, v55
	ds_read2st64_b32 v[92:93], v58 offset0:80 offset1:84
	s_waitcnt lgkmcnt(2)
	v_fmac_f32_e32 v8, v88, v40
	v_fmac_f32_e32 v9, v88, v39
	v_fmac_f32_e32 v10, v88, v38
	v_fmac_f32_e32 v11, v88, v37
	v_fmac_f32_e32 v12, v88, v36
	v_fmac_f32_e32 v13, v88, v35
	v_fmac_f32_e32 v14, v88, v34
	v_fmac_f32_e32 v15, v88, v33
	v_fmac_f32_e32 v16, v88, v32
	v_fmac_f32_e32 v17, v88, v31
	v_fmac_f32_e32 v82, v88, v30
	v_fmac_f32_e32 v83, v88, v29
	v_fmac_f32_e32 v84, v88, v28
	v_fmac_f32_e32 v85, v88, v27
	v_fmac_f32_e32 v86, v88, v26
	v_fmac_f32_e32 v87, v88, v25
	v_fma_f32 v88, v88, v24, v55
	v_fmac_f32_e32 v8, v89, v41
	v_fmac_f32_e32 v9, v89, v40
	v_fmac_f32_e32 v10, v89, v39
	v_fmac_f32_e32 v11, v89, v38
	v_fmac_f32_e32 v12, v89, v37
	v_fmac_f32_e32 v13, v89, v36
	v_fmac_f32_e32 v14, v89, v35
	v_fmac_f32_e32 v15, v89, v34
	v_fmac_f32_e32 v16, v89, v33
	v_fmac_f32_e32 v17, v89, v32
	v_fmac_f32_e32 v82, v89, v31
	v_fmac_f32_e32 v83, v89, v30
	v_fmac_f32_e32 v84, v89, v29
	v_fmac_f32_e32 v85, v89, v28
	v_fmac_f32_e32 v86, v89, v27
	v_fmac_f32_e32 v87, v89, v26
	v_fmac_f32_e32 v88, v89, v25
	v_fma_f32 v89, v89, v24, v55
	ds_read2st64_b32 v[94:95], v58 offset0:88 offset1:92
	s_waitcnt lgkmcnt(2)
	v_fmac_f32_e32 v8, v90, v42
	v_fmac_f32_e32 v9, v90, v41
	v_fmac_f32_e32 v10, v90, v40
	v_fmac_f32_e32 v11, v90, v39
	v_fmac_f32_e32 v12, v90, v38
	v_fmac_f32_e32 v13, v90, v37
	v_fmac_f32_e32 v14, v90, v36
	v_fmac_f32_e32 v15, v90, v35
	v_fmac_f32_e32 v16, v90, v34
	v_fmac_f32_e32 v17, v90, v33
	v_fmac_f32_e32 v82, v90, v32
	v_fmac_f32_e32 v83, v90, v31
	v_fmac_f32_e32 v84, v90, v30
	v_fmac_f32_e32 v85, v90, v29
	v_fmac_f32_e32 v86, v90, v28
	v_fmac_f32_e32 v87, v90, v27
	v_fmac_f32_e32 v88, v90, v26
	v_fmac_f32_e32 v89, v90, v25
	v_fma_f32 v90, v90, v24, v55
	v_fmac_f32_e32 v8, v91, v43
	v_fmac_f32_e32 v9, v91, v42
	v_fmac_f32_e32 v10, v91, v41
	v_fmac_f32_e32 v11, v91, v40
	v_fmac_f32_e32 v12, v91, v39
	v_fmac_f32_e32 v13, v91, v38
	v_fmac_f32_e32 v14, v91, v37
	v_fmac_f32_e32 v15, v91, v36
	v_fmac_f32_e32 v16, v91, v35
	v_fmac_f32_e32 v17, v91, v34
	v_fmac_f32_e32 v82, v91, v33
	v_fmac_f32_e32 v83, v91, v32
	v_fmac_f32_e32 v84, v91, v31
	v_fmac_f32_e32 v85, v91, v30
	v_fmac_f32_e32 v86, v91, v29
	v_fmac_f32_e32 v87, v91, v28
	v_fmac_f32_e32 v88, v91, v27
	v_fmac_f32_e32 v89, v91, v26
	v_fmac_f32_e32 v90, v91, v25
	v_fma_f32 v91, v91, v24, v55
	ds_read2st64_b32 v[96:97], v58 offset0:96 offset1:100
	s_waitcnt lgkmcnt(2)
	v_fmac_f32_e32 v8, v92, v44
	v_fmac_f32_e32 v9, v92, v43
	v_fmac_f32_e32 v10, v92, v42
	v_fmac_f32_e32 v11, v92, v41
	v_fmac_f32_e32 v12, v92, v40
	v_fmac_f32_e32 v13, v92, v39
	v_fmac_f32_e32 v14, v92, v38
	v_fmac_f32_e32 v15, v92, v37
	v_fmac_f32_e32 v16, v92, v36
	v_fmac_f32_e32 v17, v92, v35
	v_fmac_f32_e32 v82, v92, v34
	v_fmac_f32_e32 v83, v92, v33
	v_fmac_f32_e32 v84, v92, v32
	v_fmac_f32_e32 v85, v92, v31
	v_fmac_f32_e32 v86, v92, v30
	v_fmac_f32_e32 v87, v92, v29
	v_fmac_f32_e32 v88, v92, v28
	v_fmac_f32_e32 v89, v92, v27
	v_fmac_f32_e32 v90, v92, v26
	v_fmac_f32_e32 v91, v92, v25
	v_fma_f32 v92, v92, v24, v55
	v_fmac_f32_e32 v8, v93, v45
	v_fmac_f32_e32 v9, v93, v44
	v_fmac_f32_e32 v10, v93, v43
	v_fmac_f32_e32 v11, v93, v42
	v_fmac_f32_e32 v12, v93, v41
	v_fmac_f32_e32 v13, v93, v40
	v_fmac_f32_e32 v14, v93, v39
	v_fmac_f32_e32 v15, v93, v38
	v_fmac_f32_e32 v16, v93, v37
	v_fmac_f32_e32 v17, v93, v36
	v_fmac_f32_e32 v82, v93, v35
	v_fmac_f32_e32 v83, v93, v34
	v_fmac_f32_e32 v84, v93, v33
	v_fmac_f32_e32 v85, v93, v32
	v_fmac_f32_e32 v86, v93, v31
	v_fmac_f32_e32 v87, v93, v30
	v_fmac_f32_e32 v88, v93, v29
	v_fmac_f32_e32 v89, v93, v28
	v_fmac_f32_e32 v90, v93, v27
	v_fmac_f32_e32 v91, v93, v26
	v_fmac_f32_e32 v92, v93, v25
	v_fma_f32 v93, v93, v24, v55
	ds_read2st64_b32 v[98:99], v58 offset0:104 offset1:108
	s_waitcnt lgkmcnt(2)
	v_fmac_f32_e32 v8, v94, v46
	v_fmac_f32_e32 v9, v94, v45
	v_fmac_f32_e32 v10, v94, v44
	v_fmac_f32_e32 v11, v94, v43
	v_fmac_f32_e32 v12, v94, v42
	v_fmac_f32_e32 v13, v94, v41
	v_fmac_f32_e32 v14, v94, v40
	v_fmac_f32_e32 v15, v94, v39
	v_fmac_f32_e32 v16, v94, v38
	v_fmac_f32_e32 v17, v94, v37
	v_fmac_f32_e32 v82, v94, v36
	v_fmac_f32_e32 v83, v94, v35
	v_fmac_f32_e32 v84, v94, v34
	v_fmac_f32_e32 v85, v94, v33
	v_fmac_f32_e32 v86, v94, v32
	v_fmac_f32_e32 v87, v94, v31
	v_fmac_f32_e32 v88, v94, v30
	v_fmac_f32_e32 v89, v94, v29
	v_fmac_f32_e32 v90, v94, v28
	v_fmac_f32_e32 v91, v94, v27
	v_fmac_f32_e32 v92, v94, v26
	v_fmac_f32_e32 v93, v94, v25
	v_fma_f32 v94, v94, v24, v55
	v_fmac_f32_e32 v8, v95, v47
	v_fmac_f32_e32 v9, v95, v46
	v_fmac_f32_e32 v10, v95, v45
	v_fmac_f32_e32 v11, v95, v44
	v_fmac_f32_e32 v12, v95, v43
	v_fmac_f32_e32 v13, v95, v42
	v_fmac_f32_e32 v14, v95, v41
	v_fmac_f32_e32 v15, v95, v40
	v_fmac_f32_e32 v16, v95, v39
	v_fmac_f32_e32 v17, v95, v38
	v_fmac_f32_e32 v82, v95, v37
	v_fmac_f32_e32 v83, v95, v36
	v_fmac_f32_e32 v84, v95, v35
	v_fmac_f32_e32 v85, v95, v34
	v_fmac_f32_e32 v86, v95, v33
	v_fmac_f32_e32 v87, v95, v32
	v_fmac_f32_e32 v88, v95, v31
	v_fmac_f32_e32 v89, v95, v30
	v_fmac_f32_e32 v90, v95, v29
	v_fmac_f32_e32 v91, v95, v28
	v_fmac_f32_e32 v92, v95, v27
	v_fmac_f32_e32 v93, v95, v26
	v_fmac_f32_e32 v94, v95, v25
	v_fma_f32 v95, v95, v24, v55
	ds_read2st64_b32 v[100:101], v58 offset0:112 offset1:116
	s_waitcnt lgkmcnt(2)
	v_fmac_f32_e32 v8, v96, v48
	v_fmac_f32_e32 v9, v96, v47
	v_fmac_f32_e32 v10, v96, v46
	v_fmac_f32_e32 v11, v96, v45
	v_fmac_f32_e32 v12, v96, v44
	v_fmac_f32_e32 v13, v96, v43
	v_fmac_f32_e32 v14, v96, v42
	v_fmac_f32_e32 v15, v96, v41
	v_fmac_f32_e32 v16, v96, v40
	v_fmac_f32_e32 v17, v96, v39
	v_fmac_f32_e32 v82, v96, v38
	v_fmac_f32_e32 v83, v96, v37
	v_fmac_f32_e32 v84, v96, v36
	v_fmac_f32_e32 v85, v96, v35
	v_fmac_f32_e32 v86, v96, v34
	v_fmac_f32_e32 v87, v96, v33
	v_fmac_f32_e32 v88, v96, v32
	v_fmac_f32_e32 v89, v96, v31
	v_fmac_f32_e32 v90, v96, v30
	v_fmac_f32_e32 v91, v96, v29
	v_fmac_f32_e32 v92, v96, v28
	v_fmac_f32_e32 v93, v96, v27
	v_fmac_f32_e32 v94, v96, v26
	v_fmac_f32_e32 v95, v96, v25
	v_fma_f32 v96, v96, v24, v55
	v_fmac_f32_e32 v8, v97, v49
	v_fmac_f32_e32 v9, v97, v48
	v_fmac_f32_e32 v10, v97, v47
	v_fmac_f32_e32 v11, v97, v46
	v_fmac_f32_e32 v12, v97, v45
	v_fmac_f32_e32 v13, v97, v44
	v_fmac_f32_e32 v14, v97, v43
	v_fmac_f32_e32 v15, v97, v42
	v_fmac_f32_e32 v16, v97, v41
	v_fmac_f32_e32 v17, v97, v40
	v_fmac_f32_e32 v82, v97, v39
	v_fmac_f32_e32 v83, v97, v38
	v_fmac_f32_e32 v84, v97, v37
	v_fmac_f32_e32 v85, v97, v36
	v_fmac_f32_e32 v86, v97, v35
	v_fmac_f32_e32 v87, v97, v34
	v_fmac_f32_e32 v88, v97, v33
	v_fmac_f32_e32 v89, v97, v32
	v_fmac_f32_e32 v90, v97, v31
	v_fmac_f32_e32 v91, v97, v30
	v_fmac_f32_e32 v92, v97, v29
	v_fmac_f32_e32 v93, v97, v28
	v_fmac_f32_e32 v94, v97, v27
	v_fmac_f32_e32 v95, v97, v26
	v_fmac_f32_e32 v96, v97, v25
	v_fma_f32 v97, v97, v24, v55
	ds_read2st64_b32 v[102:103], v58 offset0:120 offset1:124
	s_waitcnt lgkmcnt(2)
	v_fmac_f32_e32 v8, v98, v50
	v_fmac_f32_e32 v9, v98, v49
	v_fmac_f32_e32 v10, v98, v48
	v_fmac_f32_e32 v11, v98, v47
	v_fmac_f32_e32 v12, v98, v46
	v_fmac_f32_e32 v13, v98, v45
	v_fmac_f32_e32 v14, v98, v44
	v_fmac_f32_e32 v15, v98, v43
	v_fmac_f32_e32 v16, v98, v42
	v_fmac_f32_e32 v17, v98, v41
	v_fmac_f32_e32 v82, v98, v40
	v_fmac_f32_e32 v83, v98, v39
	v_fmac_f32_e32 v84, v98, v38
	v_fmac_f32_e32 v85, v98, v37
	v_fmac_f32_e32 v86, v98, v36
	v_fmac_f32_e32 v87, v98, v35
	v_fmac_f32_e32 v88, v98, v34
	v_fmac_f32_e32 v89, v98, v33
	v_fmac_f32_e32 v90, v98, v32
	v_fmac_f32_e32 v91, v98, v31
	v_fmac_f32_e32 v92, v98, v30
	v_fmac_f32_e32 v93, v98, v29
	v_fmac_f32_e32 v94, v98, v28
	v_fmac_f32_e32 v95, v98, v27
	v_fmac_f32_e32 v96, v98, v26
	v_fmac_f32_e32 v97, v98, v25
	v_fma_f32 v98, v98, v24, v55
	v_fmac_f32_e32 v8, v99, v51
	v_fmac_f32_e32 v9, v99, v50
	v_fmac_f32_e32 v10, v99, v49
	v_fmac_f32_e32 v11, v99, v48
	v_fmac_f32_e32 v12, v99, v47
	v_fmac_f32_e32 v13, v99, v46
	v_fmac_f32_e32 v14, v99, v45
	v_fmac_f32_e32 v15, v99, v44
	v_fmac_f32_e32 v16, v99, v43
	v_fmac_f32_e32 v17, v99, v42
	v_fmac_f32_e32 v82, v99, v41
	v_fmac_f32_e32 v83, v99, v40
	v_fmac_f32_e32 v84, v99, v39
	v_fmac_f32_e32 v85, v99, v38
	v_fmac_f32_e32 v86, v99, v37
	v_fmac_f32_e32 v87, v99, v36
	v_fmac_f32_e32 v88, v99, v35
	v_fmac_f32_e32 v89, v99, v34
	v_fmac_f32_e32 v90, v99, v33
	v_fmac_f32_e32 v91, v99, v32
	v_fmac_f32_e32 v92, v99, v31
	v_fmac_f32_e32 v93, v99, v30
	v_fmac_f32_e32 v94, v99, v29
	v_fmac_f32_e32 v95, v99, v28
	v_fmac_f32_e32 v96, v99, v27
	v_fmac_f32_e32 v97, v99, v26
	v_fmac_f32_e32 v98, v99, v25
	v_fma_f32 v99, v99, v24, v55
	ds_read2st64_b32 v[104:105], v58 offset0:128 offset1:132
	s_waitcnt lgkmcnt(2)
	v_fmac_f32_e32 v8, v100, v52
	v_fmac_f32_e32 v9, v100, v51
	v_fmac_f32_e32 v10, v100, v50
	v_fmac_f32_e32 v11, v100, v49
	v_fmac_f32_e32 v12, v100, v48
	v_fmac_f32_e32 v13, v100, v47
	v_fmac_f32_e32 v14, v100, v46
	v_fmac_f32_e32 v15, v100, v45
	v_fmac_f32_e32 v16, v100, v44
	v_fmac_f32_e32 v17, v100, v43
	v_fmac_f32_e32 v82, v100, v42
	v_fmac_f32_e32 v83, v100, v41
	v_fmac_f32_e32 v84, v100, v40
	v_fmac_f32_e32 v85, v100, v39
	v_fmac_f32_e32 v86, v100, v38
	v_fmac_f32_e32 v87, v100, v37
	v_fmac_f32_e32 v88, v100, v36
	v_fmac_f32_e32 v89, v100, v35
	v_fmac_f32_e32 v90, v100, v34
	v_fmac_f32_e32 v91, v100, v33
	v_fmac_f32_e32 v92, v100, v32
	v_fmac_f32_e32 v93, v100, v31
	v_fmac_f32_e32 v94, v100, v30
	v_fmac_f32_e32 v95, v100, v29
	v_fmac_f32_e32 v96, v100, v28
	v_fmac_f32_e32 v97, v100, v27
	v_fmac_f32_e32 v98, v100, v26
	v_fmac_f32_e32 v99, v100, v25
	v_fma_f32 v100, v100, v24, v55
	v_fmac_f32_e32 v8, v101, v53
	v_fmac_f32_e32 v9, v101, v52
	v_fmac_f32_e32 v10, v101, v51
	v_fmac_f32_e32 v11, v101, v50
	v_fmac_f32_e32 v12, v101, v49
	v_fmac_f32_e32 v13, v101, v48
	v_fmac_f32_e32 v14, v101, v47
	v_fmac_f32_e32 v15, v101, v46
	v_fmac_f32_e32 v16, v101, v45
	v_fmac_f32_e32 v17, v101, v44
	v_fmac_f32_e32 v82, v101, v43
	v_fmac_f32_e32 v83, v101, v42
	v_fmac_f32_e32 v84, v101, v41
	v_fmac_f32_e32 v85, v101, v40
	v_fmac_f32_e32 v86, v101, v39
	v_fmac_f32_e32 v87, v101, v38
	v_fmac_f32_e32 v88, v101, v37
	v_fmac_f32_e32 v89, v101, v36
	v_fmac_f32_e32 v90, v101, v35
	v_fmac_f32_e32 v91, v101, v34
	v_fmac_f32_e32 v92, v101, v33
	v_fmac_f32_e32 v93, v101, v32
	v_fmac_f32_e32 v94, v101, v31
	v_fmac_f32_e32 v95, v101, v30
	v_fmac_f32_e32 v96, v101, v29
	v_fmac_f32_e32 v97, v101, v28
	v_fmac_f32_e32 v98, v101, v27
	v_fmac_f32_e32 v99, v101, v26
	v_fmac_f32_e32 v100, v101, v25
	v_fma_f32 v101, v101, v24, v55
	s_waitcnt lgkmcnt(1)
	v_fmac_f32_e32 v8, v102, v54
	v_fmac_f32_e32 v9, v102, v53
	v_fmac_f32_e32 v10, v102, v52
	v_fmac_f32_e32 v11, v102, v51
	v_fmac_f32_e32 v12, v102, v50
	v_fmac_f32_e32 v13, v102, v49
	v_fmac_f32_e32 v14, v102, v48
	v_fmac_f32_e32 v15, v102, v47
	v_fmac_f32_e32 v16, v102, v46
	v_fmac_f32_e32 v17, v102, v45
	v_fmac_f32_e32 v82, v102, v44
	v_fmac_f32_e32 v83, v102, v43
	v_fmac_f32_e32 v84, v102, v42
	v_fmac_f32_e32 v85, v102, v41
	v_fmac_f32_e32 v86, v102, v40
	v_fmac_f32_e32 v87, v102, v39
	v_fmac_f32_e32 v88, v102, v38
	v_fmac_f32_e32 v89, v102, v37
	v_fmac_f32_e32 v90, v102, v36
	v_fmac_f32_e32 v91, v102, v35
	v_fmac_f32_e32 v92, v102, v34
	v_fmac_f32_e32 v93, v102, v33
	v_fmac_f32_e32 v94, v102, v32
	v_fmac_f32_e32 v95, v102, v31
	v_fmac_f32_e32 v96, v102, v30
	v_fmac_f32_e32 v97, v102, v29
	v_fmac_f32_e32 v98, v102, v28
	v_fmac_f32_e32 v99, v102, v27
	v_fmac_f32_e32 v100, v102, v26
	v_fmac_f32_e32 v101, v102, v25
	v_fma_f32 v102, v102, v24, v55
	v_fmac_f32_e32 v9, v103, v54
	v_fmac_f32_e32 v10, v103, v53
	v_fmac_f32_e32 v11, v103, v52
	v_fmac_f32_e32 v12, v103, v51
	v_fmac_f32_e32 v13, v103, v50
	v_fmac_f32_e32 v14, v103, v49
	v_fmac_f32_e32 v15, v103, v48
	v_fmac_f32_e32 v16, v103, v47
	v_fmac_f32_e32 v17, v103, v46
	v_fmac_f32_e32 v82, v103, v45
	v_fmac_f32_e32 v83, v103, v44
	v_fmac_f32_e32 v84, v103, v43
	v_fmac_f32_e32 v85, v103, v42
	v_fmac_f32_e32 v86, v103, v41
	v_fmac_f32_e32 v87, v103, v40
	v_fmac_f32_e32 v88, v103, v39
	v_fmac_f32_e32 v89, v103, v38
	v_fmac_f32_e32 v90, v103, v37
	v_fmac_f32_e32 v91, v103, v36
	v_fmac_f32_e32 v92, v103, v35
	v_fmac_f32_e32 v93, v103, v34
	v_fmac_f32_e32 v94, v103, v33
	v_fmac_f32_e32 v95, v103, v32
	v_fmac_f32_e32 v96, v103, v31
	v_fmac_f32_e32 v97, v103, v30
	v_fmac_f32_e32 v98, v103, v29
	v_fmac_f32_e32 v99, v103, v28
	v_fmac_f32_e32 v100, v103, v27
	v_fmac_f32_e32 v101, v103, v26
	v_fmac_f32_e32 v102, v103, v25
	v_fma_f32 v103, v103, v24, v55
	s_waitcnt lgkmcnt(0)
	v_fmac_f32_e32 v11, v104, v53
	v_fmac_f32_e32 v12, v104, v52
	v_fmac_f32_e32 v13, v104, v51
	v_fmac_f32_e32 v14, v104, v50
	v_fmac_f32_e32 v15, v104, v49
	v_fmac_f32_e32 v16, v104, v48
	v_fmac_f32_e32 v17, v104, v47
	v_fmac_f32_e32 v82, v104, v46
	v_fmac_f32_e32 v83, v104, v45
	v_fmac_f32_e32 v84, v104, v44
	v_fmac_f32_e32 v85, v104, v43
	v_fmac_f32_e32 v86, v104, v42
	v_fmac_f32_e32 v87, v104, v41
	v_fmac_f32_e32 v88, v104, v40
	v_fmac_f32_e32 v89, v104, v39
	v_fmac_f32_e32 v90, v104, v38
	v_fmac_f32_e32 v91, v104, v37
	v_fmac_f32_e32 v92, v104, v36
	v_fmac_f32_e32 v93, v104, v35
	v_fmac_f32_e32 v94, v104, v34
	v_fmac_f32_e32 v95, v104, v33
	v_fmac_f32_e32 v96, v104, v32
	v_fmac_f32_e32 v97, v104, v31
	v_fmac_f32_e32 v98, v104, v30
	v_fmac_f32_e32 v99, v104, v29
	v_fmac_f32_e32 v100, v104, v28
	v_fmac_f32_e32 v101, v104, v27
	v_fmac_f32_e32 v102, v104, v26
	v_fmac_f32_e32 v103, v104, v25
	v_fmac_f32_e32 v10, v104, v54
	v_fmac_f32_e32 v11, v105, v54
	v_fmac_f32_e32 v12, v105, v53
	v_fmac_f32_e32 v13, v105, v52
	v_fmac_f32_e32 v14, v105, v51
	v_fmac_f32_e32 v15, v105, v50
	v_fmac_f32_e32 v16, v105, v49
	v_fmac_f32_e32 v17, v105, v48
	v_fmac_f32_e32 v82, v105, v47
	v_fmac_f32_e32 v83, v105, v46
	v_fmac_f32_e32 v84, v105, v45
	v_fmac_f32_e32 v85, v105, v44
	v_fmac_f32_e32 v86, v105, v43
	v_fmac_f32_e32 v87, v105, v42
	v_fmac_f32_e32 v88, v105, v41
	v_fmac_f32_e32 v89, v105, v40
	v_fmac_f32_e32 v90, v105, v39
	v_fmac_f32_e32 v91, v105, v38
	v_fmac_f32_e32 v92, v105, v37
	v_fmac_f32_e32 v93, v105, v36
	v_fmac_f32_e32 v94, v105, v35
	v_fmac_f32_e32 v95, v105, v34
	v_fmac_f32_e32 v96, v105, v33
	v_fmac_f32_e32 v97, v105, v32
	v_fmac_f32_e32 v98, v105, v31
	v_fmac_f32_e32 v99, v105, v30
	v_fmac_f32_e32 v100, v105, v29
	v_fmac_f32_e32 v101, v105, v28
	v_fmac_f32_e32 v102, v105, v27
	v_fmac_f32_e32 v103, v105, v26
	ds_read2st64_b32 v[104:105], v58 offset0:136 offset1:140
	s_mov_b32 s4, 0
	s_waitcnt lgkmcnt(0)
	v_fmac_f32_e32 v13, v104, v53
	v_fmac_f32_e32 v14, v104, v52
	v_fmac_f32_e32 v15, v104, v51
	v_fmac_f32_e32 v16, v104, v50
	v_fmac_f32_e32 v17, v104, v49
	v_fmac_f32_e32 v82, v104, v48
	v_fmac_f32_e32 v83, v104, v47
	v_fmac_f32_e32 v84, v104, v46
	v_fmac_f32_e32 v85, v104, v45
	v_fmac_f32_e32 v86, v104, v44
	v_fmac_f32_e32 v87, v104, v43
	v_fmac_f32_e32 v88, v104, v42
	v_fmac_f32_e32 v89, v104, v41
	v_fmac_f32_e32 v90, v104, v40
	v_fmac_f32_e32 v91, v104, v39
	v_fmac_f32_e32 v92, v104, v38
	v_fmac_f32_e32 v93, v104, v37
	v_fmac_f32_e32 v94, v104, v36
	v_fmac_f32_e32 v95, v104, v35
	v_fmac_f32_e32 v96, v104, v34
	v_fmac_f32_e32 v97, v104, v33
	v_fmac_f32_e32 v98, v104, v32
	v_fmac_f32_e32 v99, v104, v31
	v_fmac_f32_e32 v100, v104, v30
	v_fmac_f32_e32 v101, v104, v29
	v_fmac_f32_e32 v102, v104, v28
	v_fmac_f32_e32 v103, v104, v27
	v_fmac_f32_e32 v12, v104, v54
	v_fmac_f32_e32 v13, v105, v54
	v_fmac_f32_e32 v14, v105, v53
	v_fmac_f32_e32 v15, v105, v52
	v_fmac_f32_e32 v16, v105, v51
	v_fmac_f32_e32 v17, v105, v50
	v_fmac_f32_e32 v82, v105, v49
	v_fmac_f32_e32 v83, v105, v48
	v_fmac_f32_e32 v84, v105, v47
	v_fmac_f32_e32 v85, v105, v46
	v_fmac_f32_e32 v86, v105, v45
	v_fmac_f32_e32 v87, v105, v44
	v_fmac_f32_e32 v88, v105, v43
	v_fmac_f32_e32 v89, v105, v42
	v_fmac_f32_e32 v90, v105, v41
	v_fmac_f32_e32 v91, v105, v40
	v_fmac_f32_e32 v92, v105, v39
	v_fmac_f32_e32 v93, v105, v38
	v_fmac_f32_e32 v94, v105, v37
	v_fmac_f32_e32 v95, v105, v36
	v_fmac_f32_e32 v96, v105, v35
	v_fmac_f32_e32 v97, v105, v34
	v_fmac_f32_e32 v98, v105, v33
	v_fmac_f32_e32 v99, v105, v32
	v_fmac_f32_e32 v100, v105, v31
	v_fmac_f32_e32 v101, v105, v30
	v_fmac_f32_e32 v102, v105, v29
	v_fmac_f32_e32 v103, v105, v28
	ds_read2st64_b32 v[104:105], v58 offset0:144 offset1:148
	s_waitcnt lgkmcnt(0)
	v_fmac_f32_e32 v15, v104, v53
	v_fmac_f32_e32 v16, v104, v52
	v_fmac_f32_e32 v17, v104, v51
	v_fmac_f32_e32 v82, v104, v50
	v_fmac_f32_e32 v83, v104, v49
	v_fmac_f32_e32 v84, v104, v48
	v_fmac_f32_e32 v85, v104, v47
	v_fmac_f32_e32 v86, v104, v46
	v_fmac_f32_e32 v87, v104, v45
	v_fmac_f32_e32 v88, v104, v44
	v_fmac_f32_e32 v89, v104, v43
	v_fmac_f32_e32 v90, v104, v42
	v_fmac_f32_e32 v91, v104, v41
	v_fmac_f32_e32 v92, v104, v40
	v_fmac_f32_e32 v93, v104, v39
	v_fmac_f32_e32 v94, v104, v38
	v_fmac_f32_e32 v95, v104, v37
	v_fmac_f32_e32 v96, v104, v36
	v_fmac_f32_e32 v97, v104, v35
	v_fmac_f32_e32 v98, v104, v34
	v_fmac_f32_e32 v99, v104, v33
	v_fmac_f32_e32 v100, v104, v32
	v_fmac_f32_e32 v101, v104, v31
	v_fmac_f32_e32 v102, v104, v30
	v_fmac_f32_e32 v103, v104, v29
	v_fmac_f32_e32 v14, v104, v54
	v_fmac_f32_e32 v15, v105, v54
	v_fmac_f32_e32 v16, v105, v53
	v_fmac_f32_e32 v17, v105, v52
	v_fmac_f32_e32 v82, v105, v51
	v_fmac_f32_e32 v83, v105, v50
	v_fmac_f32_e32 v84, v105, v49
	v_fmac_f32_e32 v85, v105, v48
	v_fmac_f32_e32 v86, v105, v47
	v_fmac_f32_e32 v87, v105, v46
	v_fmac_f32_e32 v88, v105, v45
	v_fmac_f32_e32 v89, v105, v44
	v_fmac_f32_e32 v90, v105, v43
	v_fmac_f32_e32 v91, v105, v42
	v_fmac_f32_e32 v92, v105, v41
	v_fmac_f32_e32 v93, v105, v40
	v_fmac_f32_e32 v94, v105, v39
	v_fmac_f32_e32 v95, v105, v38
	v_fmac_f32_e32 v96, v105, v37
	v_fmac_f32_e32 v97, v105, v36
	v_fmac_f32_e32 v98, v105, v35
	v_fmac_f32_e32 v99, v105, v34
	v_fmac_f32_e32 v100, v105, v33
	v_fmac_f32_e32 v101, v105, v32
	v_fmac_f32_e32 v102, v105, v31
	v_fmac_f32_e32 v103, v105, v30
	ds_read2st64_b32 v[104:105], v58 offset0:152 offset1:156
	s_waitcnt lgkmcnt(0)
	v_fmac_f32_e32 v17, v104, v53
	v_fmac_f32_e32 v82, v104, v52
	v_fmac_f32_e32 v83, v104, v51
	v_fmac_f32_e32 v84, v104, v50
	v_fmac_f32_e32 v85, v104, v49
	v_fmac_f32_e32 v86, v104, v48
	v_fmac_f32_e32 v87, v104, v47
	v_fmac_f32_e32 v88, v104, v46
	v_fmac_f32_e32 v89, v104, v45
	v_fmac_f32_e32 v90, v104, v44
	v_fmac_f32_e32 v91, v104, v43
	v_fmac_f32_e32 v92, v104, v42
	v_fmac_f32_e32 v93, v104, v41
	v_fmac_f32_e32 v94, v104, v40
	v_fmac_f32_e32 v95, v104, v39
	v_fmac_f32_e32 v96, v104, v38
	v_fmac_f32_e32 v97, v104, v37
	v_fmac_f32_e32 v98, v104, v36
	v_fmac_f32_e32 v99, v104, v35
	v_fmac_f32_e32 v100, v104, v34
	v_fmac_f32_e32 v101, v104, v33
	v_fmac_f32_e32 v102, v104, v32
	v_fmac_f32_e32 v103, v104, v31
	v_fmac_f32_e32 v16, v104, v54
	v_fmac_f32_e32 v17, v105, v54
	v_fmac_f32_e32 v82, v105, v53
	v_fmac_f32_e32 v83, v105, v52
	v_fmac_f32_e32 v84, v105, v51
	v_fmac_f32_e32 v85, v105, v50
	v_fmac_f32_e32 v86, v105, v49
	v_fmac_f32_e32 v87, v105, v48
	v_fmac_f32_e32 v88, v105, v47
	v_fmac_f32_e32 v89, v105, v46
	v_fmac_f32_e32 v90, v105, v45
	v_fmac_f32_e32 v91, v105, v44
	v_fmac_f32_e32 v92, v105, v43
	v_fmac_f32_e32 v93, v105, v42
	v_fmac_f32_e32 v94, v105, v41
	v_fmac_f32_e32 v95, v105, v40
	v_fmac_f32_e32 v96, v105, v39
	v_fmac_f32_e32 v97, v105, v38
	v_fmac_f32_e32 v98, v105, v37
	v_fmac_f32_e32 v99, v105, v36
	v_fmac_f32_e32 v100, v105, v35
	v_fmac_f32_e32 v101, v105, v34
	v_fmac_f32_e32 v102, v105, v33
	v_fmac_f32_e32 v103, v105, v32
	ds_read2st64_b32 v[104:105], v58 offset0:160 offset1:164
	s_waitcnt lgkmcnt(0)
	v_fmac_f32_e32 v83, v104, v53
	v_fmac_f32_e32 v84, v104, v52
	v_fmac_f32_e32 v85, v104, v51
	v_fmac_f32_e32 v86, v104, v50
	v_fmac_f32_e32 v87, v104, v49
	v_fmac_f32_e32 v88, v104, v48
	v_fmac_f32_e32 v89, v104, v47
	v_fmac_f32_e32 v90, v104, v46
	v_fmac_f32_e32 v91, v104, v45
	v_fmac_f32_e32 v92, v104, v44
	v_fmac_f32_e32 v93, v104, v43
	v_fmac_f32_e32 v94, v104, v42
	v_fmac_f32_e32 v95, v104, v41
	v_fmac_f32_e32 v96, v104, v40
	v_fmac_f32_e32 v97, v104, v39
	v_fmac_f32_e32 v98, v104, v38
	v_fmac_f32_e32 v99, v104, v37
	v_fmac_f32_e32 v100, v104, v36
	v_fmac_f32_e32 v101, v104, v35
	v_fmac_f32_e32 v102, v104, v34
	v_fmac_f32_e32 v103, v104, v33
	v_fmac_f32_e32 v82, v104, v54
	v_fmac_f32_e32 v83, v105, v54
	v_fmac_f32_e32 v84, v105, v53
	v_fmac_f32_e32 v85, v105, v52
	v_fmac_f32_e32 v86, v105, v51
	v_fmac_f32_e32 v87, v105, v50
	v_fmac_f32_e32 v88, v105, v49
	v_fmac_f32_e32 v89, v105, v48
	v_fmac_f32_e32 v90, v105, v47
	v_fmac_f32_e32 v91, v105, v46
	v_fmac_f32_e32 v92, v105, v45
	v_fmac_f32_e32 v93, v105, v44
	v_fmac_f32_e32 v94, v105, v43
	v_fmac_f32_e32 v95, v105, v42
	v_fmac_f32_e32 v96, v105, v41
	v_fmac_f32_e32 v97, v105, v40
	v_fmac_f32_e32 v98, v105, v39
	v_fmac_f32_e32 v99, v105, v38
	v_fmac_f32_e32 v100, v105, v37
	v_fmac_f32_e32 v101, v105, v36
	v_fmac_f32_e32 v102, v105, v35
	v_fmac_f32_e32 v103, v105, v34
	ds_read2st64_b32 v[104:105], v58 offset0:168 offset1:172
	s_waitcnt lgkmcnt(0)
	v_fmac_f32_e32 v85, v104, v53
	v_fmac_f32_e32 v86, v104, v52
	v_fmac_f32_e32 v87, v104, v51
	v_fmac_f32_e32 v88, v104, v50
	v_fmac_f32_e32 v89, v104, v49
	v_fmac_f32_e32 v90, v104, v48
	v_fmac_f32_e32 v91, v104, v47
	v_fmac_f32_e32 v92, v104, v46
	v_fmac_f32_e32 v93, v104, v45
	v_fmac_f32_e32 v94, v104, v44
	v_fmac_f32_e32 v95, v104, v43
	v_fmac_f32_e32 v96, v104, v42
	v_fmac_f32_e32 v97, v104, v41
	v_fmac_f32_e32 v98, v104, v40
	v_fmac_f32_e32 v99, v104, v39
	v_fmac_f32_e32 v100, v104, v38
	v_fmac_f32_e32 v101, v104, v37
	v_fmac_f32_e32 v102, v104, v36
	v_fmac_f32_e32 v103, v104, v35
	v_fmac_f32_e32 v84, v104, v54
	v_fmac_f32_e32 v85, v105, v54
	v_fmac_f32_e32 v86, v105, v53
	v_fmac_f32_e32 v87, v105, v52
	v_fmac_f32_e32 v88, v105, v51
	v_fmac_f32_e32 v89, v105, v50
	v_fmac_f32_e32 v90, v105, v49
	v_fmac_f32_e32 v91, v105, v48
	v_fmac_f32_e32 v92, v105, v47
	v_fmac_f32_e32 v93, v105, v46
	v_fmac_f32_e32 v94, v105, v45
	v_fmac_f32_e32 v95, v105, v44
	v_fmac_f32_e32 v96, v105, v43
	v_fmac_f32_e32 v97, v105, v42
	v_fmac_f32_e32 v98, v105, v41
	v_fmac_f32_e32 v99, v105, v40
	v_fmac_f32_e32 v100, v105, v39
	v_fmac_f32_e32 v101, v105, v38
	v_fmac_f32_e32 v102, v105, v37
	v_fmac_f32_e32 v103, v105, v36
	ds_read2st64_b32 v[104:105], v58 offset0:176 offset1:180
	s_waitcnt lgkmcnt(0)
	v_fmac_f32_e32 v87, v104, v53
	v_fmac_f32_e32 v88, v104, v52
	v_fmac_f32_e32 v89, v104, v51
	v_fmac_f32_e32 v90, v104, v50
	v_fmac_f32_e32 v91, v104, v49
	v_fmac_f32_e32 v92, v104, v48
	v_fmac_f32_e32 v93, v104, v47
	v_fmac_f32_e32 v94, v104, v46
	v_fmac_f32_e32 v95, v104, v45
	v_fmac_f32_e32 v96, v104, v44
	v_fmac_f32_e32 v97, v104, v43
	v_fmac_f32_e32 v98, v104, v42
	v_fmac_f32_e32 v99, v104, v41
	v_fmac_f32_e32 v100, v104, v40
	v_fmac_f32_e32 v101, v104, v39
	v_fmac_f32_e32 v102, v104, v38
	v_fmac_f32_e32 v103, v104, v37
	v_fmac_f32_e32 v86, v104, v54
	v_fmac_f32_e32 v87, v105, v54
	v_fmac_f32_e32 v88, v105, v53
	v_fmac_f32_e32 v89, v105, v52
	v_fmac_f32_e32 v90, v105, v51
	v_fmac_f32_e32 v91, v105, v50
	v_fmac_f32_e32 v92, v105, v49
	v_fmac_f32_e32 v93, v105, v48
	v_fmac_f32_e32 v94, v105, v47
	v_fmac_f32_e32 v95, v105, v46
	v_fmac_f32_e32 v96, v105, v45
	v_fmac_f32_e32 v97, v105, v44
	v_fmac_f32_e32 v98, v105, v43
	v_fmac_f32_e32 v99, v105, v42
	v_fmac_f32_e32 v100, v105, v41
	v_fmac_f32_e32 v101, v105, v40
	v_fmac_f32_e32 v102, v105, v39
	v_fmac_f32_e32 v103, v105, v38
	ds_read2st64_b32 v[104:105], v58 offset0:184 offset1:188
	s_waitcnt lgkmcnt(0)
	v_fmac_f32_e32 v89, v104, v53
	v_fmac_f32_e32 v90, v104, v52
	v_fmac_f32_e32 v91, v104, v51
	v_fmac_f32_e32 v92, v104, v50
	v_fmac_f32_e32 v93, v104, v49
	v_fmac_f32_e32 v94, v104, v48
	v_fmac_f32_e32 v95, v104, v47
	v_fmac_f32_e32 v96, v104, v46
	v_fmac_f32_e32 v97, v104, v45
	v_fmac_f32_e32 v98, v104, v44
	v_fmac_f32_e32 v99, v104, v43
	v_fmac_f32_e32 v100, v104, v42
	v_fmac_f32_e32 v101, v104, v41
	v_fmac_f32_e32 v102, v104, v40
	v_fmac_f32_e32 v103, v104, v39
	v_fmac_f32_e32 v88, v104, v54
	v_fmac_f32_e32 v89, v105, v54
	v_fmac_f32_e32 v90, v105, v53
	v_fmac_f32_e32 v91, v105, v52
	v_fmac_f32_e32 v92, v105, v51
	v_fmac_f32_e32 v93, v105, v50
	v_fmac_f32_e32 v94, v105, v49
	v_fmac_f32_e32 v95, v105, v48
	v_fmac_f32_e32 v96, v105, v47
	v_fmac_f32_e32 v97, v105, v46
	v_fmac_f32_e32 v98, v105, v45
	v_fmac_f32_e32 v99, v105, v44
	v_fmac_f32_e32 v100, v105, v43
	v_fmac_f32_e32 v101, v105, v42
	v_fmac_f32_e32 v102, v105, v41
	v_fmac_f32_e32 v103, v105, v40
	ds_read2st64_b32 v[104:105], v58 offset0:192 offset1:196
	s_waitcnt lgkmcnt(0)
	v_fmac_f32_e32 v91, v104, v53
	v_fmac_f32_e32 v92, v104, v52
	v_fmac_f32_e32 v93, v104, v51
	v_fmac_f32_e32 v94, v104, v50
	v_fmac_f32_e32 v95, v104, v49
	v_fmac_f32_e32 v96, v104, v48
	v_fmac_f32_e32 v97, v104, v47
	v_fmac_f32_e32 v98, v104, v46
	v_fmac_f32_e32 v99, v104, v45
	v_fmac_f32_e32 v100, v104, v44
	v_fmac_f32_e32 v101, v104, v43
	v_fmac_f32_e32 v102, v104, v42
	v_fmac_f32_e32 v103, v104, v41
	v_fmac_f32_e32 v90, v104, v54
	v_fmac_f32_e32 v91, v105, v54
	v_fmac_f32_e32 v92, v105, v53
	v_fmac_f32_e32 v93, v105, v52
	v_fmac_f32_e32 v94, v105, v51
	v_fmac_f32_e32 v95, v105, v50
	v_fmac_f32_e32 v96, v105, v49
	v_fmac_f32_e32 v97, v105, v48
	v_fmac_f32_e32 v98, v105, v47
	v_fmac_f32_e32 v99, v105, v46
	v_fmac_f32_e32 v100, v105, v45
	v_fmac_f32_e32 v101, v105, v44
	v_fmac_f32_e32 v102, v105, v43
	v_fmac_f32_e32 v103, v105, v42
	ds_read2st64_b32 v[104:105], v58 offset0:200 offset1:204
	s_waitcnt lgkmcnt(0)
	v_fmac_f32_e32 v93, v104, v53
	v_fmac_f32_e32 v94, v104, v52
	v_fmac_f32_e32 v95, v104, v51
	v_fmac_f32_e32 v96, v104, v50
	v_fmac_f32_e32 v97, v104, v49
	v_fmac_f32_e32 v98, v104, v48
	v_fmac_f32_e32 v99, v104, v47
	v_fmac_f32_e32 v100, v104, v46
	v_fmac_f32_e32 v101, v104, v45
	v_fmac_f32_e32 v102, v104, v44
	v_fmac_f32_e32 v103, v104, v43
	v_fmac_f32_e32 v92, v104, v54
	v_fmac_f32_e32 v93, v105, v54
	v_fmac_f32_e32 v94, v105, v53
	v_fmac_f32_e32 v95, v105, v52
	v_fmac_f32_e32 v96, v105, v51
	v_fmac_f32_e32 v97, v105, v50
	v_fmac_f32_e32 v98, v105, v49
	v_fmac_f32_e32 v99, v105, v48
	v_fmac_f32_e32 v100, v105, v47
	v_fmac_f32_e32 v101, v105, v46
	v_fmac_f32_e32 v102, v105, v45
	v_fmac_f32_e32 v103, v105, v44
	ds_read2st64_b32 v[104:105], v58 offset0:208 offset1:212
	s_waitcnt lgkmcnt(0)
	v_fmac_f32_e32 v95, v104, v53
	v_fmac_f32_e32 v96, v104, v52
	v_fmac_f32_e32 v97, v104, v51
	v_fmac_f32_e32 v98, v104, v50
	v_fmac_f32_e32 v99, v104, v49
	v_fmac_f32_e32 v100, v104, v48
	v_fmac_f32_e32 v101, v104, v47
	v_fmac_f32_e32 v102, v104, v46
	v_fmac_f32_e32 v103, v104, v45
	v_fmac_f32_e32 v94, v104, v54
	v_fmac_f32_e32 v95, v105, v54
	v_fmac_f32_e32 v96, v105, v53
	v_fmac_f32_e32 v97, v105, v52
	v_fmac_f32_e32 v98, v105, v51
	v_fmac_f32_e32 v99, v105, v50
	v_fmac_f32_e32 v100, v105, v49
	v_fmac_f32_e32 v101, v105, v48
	v_fmac_f32_e32 v102, v105, v47
	v_fmac_f32_e32 v103, v105, v46
	ds_read2st64_b32 v[104:105], v58 offset0:216 offset1:220
	s_waitcnt lgkmcnt(0)
	v_fmac_f32_e32 v97, v104, v53
	v_fmac_f32_e32 v98, v104, v52
	v_fmac_f32_e32 v99, v104, v51
	v_fmac_f32_e32 v100, v104, v50
	v_fmac_f32_e32 v101, v104, v49
	v_fmac_f32_e32 v102, v104, v48
	v_fmac_f32_e32 v103, v104, v47
	v_fmac_f32_e32 v96, v104, v54
	v_fmac_f32_e32 v97, v105, v54
	v_fmac_f32_e32 v98, v105, v53
	v_fmac_f32_e32 v99, v105, v52
	v_fmac_f32_e32 v100, v105, v51
	v_fmac_f32_e32 v101, v105, v50
	v_fmac_f32_e32 v102, v105, v49
	v_fmac_f32_e32 v103, v105, v48
	ds_read2st64_b32 v[104:105], v58 offset0:224 offset1:228
	s_waitcnt lgkmcnt(0)
	v_fmac_f32_e32 v99, v104, v53
	v_fmac_f32_e32 v100, v104, v52
	v_fmac_f32_e32 v101, v104, v51
	v_fmac_f32_e32 v102, v104, v50
	v_fmac_f32_e32 v103, v104, v49
	v_fmac_f32_e32 v98, v104, v54
	v_fmac_f32_e32 v99, v105, v54
	v_fmac_f32_e32 v100, v105, v53
	v_fmac_f32_e32 v101, v105, v52
	v_fmac_f32_e32 v102, v105, v51
	v_fmac_f32_e32 v103, v105, v50
	ds_read2st64_b32 v[104:105], v58 offset0:232 offset1:236
	s_waitcnt lgkmcnt(0)
	v_fmac_f32_e32 v101, v104, v53
	v_fmac_f32_e32 v102, v104, v52
	v_fmac_f32_e32 v103, v104, v51
	v_fmac_f32_e32 v100, v104, v54
	v_fmac_f32_e32 v101, v105, v54
	v_fmac_f32_e32 v102, v105, v53
	v_fmac_f32_e32 v103, v105, v52
	ds_read2st64_b32 v[104:105], v58 offset0:240 offset1:244
	s_waitcnt lgkmcnt(0)
	s_barrier
	v_fmac_f32_e32 v103, v104, v53
	v_fmac_f32_e32 v102, v104, v54
	v_fmac_f32_e32 v103, v105, v54
	ds_write2st64_b32 v58, v8, v9 offset1:4
	ds_write2st64_b32 v58, v10, v11 offset0:8 offset1:12
	ds_write2st64_b32 v58, v12, v13 offset0:16 offset1:20
	ds_write2st64_b32 v58, v14, v15 offset0:24 offset1:28
	ds_write2st64_b32 v58, v16, v17 offset0:32 offset1:36
	ds_write2st64_b32 v58, v82, v83 offset0:40 offset1:44
	ds_write2st64_b32 v58, v84, v85 offset0:48 offset1:52
	ds_write2st64_b32 v58, v86, v87 offset0:56 offset1:60
	ds_write2st64_b32 v58, v88, v89 offset0:64 offset1:68
	ds_write2st64_b32 v58, v90, v91 offset0:72 offset1:76
	ds_write2st64_b32 v58, v92, v93 offset0:80 offset1:84
	ds_write2st64_b32 v58, v94, v95 offset0:88 offset1:92
	ds_write2st64_b32 v58, v96, v97 offset0:96 offset1:100
	ds_write2st64_b32 v58, v98, v99 offset0:104 offset1:108
	ds_write2st64_b32 v58, v100, v101 offset0:112 offset1:116
	ds_write2st64_b32 v58, v102, v103 offset0:120 offset1:124
	v_mov_b32_e32 v8, v72
	s_waitcnt lgkmcnt(0)
	s_barrier
	s_waitcnt vmcnt(0)
